# in-proj dt units permuted so pad-row zero-fill and extra units land on workgroups without tail units
# speedup vs baseline: 1.0451x; 1.0106x over previous
; #define LAS __attribute__((address_space(3)))
; __device__ __forceinline__ int tidx() { int t = threadIdx.x; asm volatile("" : "+v"(t)); return t; }
; __device__ __forceinline__ void dt_units(LAS unsigned char* lds, const bf16_t* xb, const bf16_t* WinT, const float* stat, const float* c1, const float* c2, float* dtbuf, int fold, bf16_t* proj, const int ufirst, const int ustride, const int uend) {
;     const int tid = tidx(), wid = tid >> 6, lane = tid & 63, fr = lane & 15, fq = lane >> 4, rb4 = wid & 3, kh = wid >> 2;
;     LAS float* red = (LAS float*)lds;
;     for (int u = ufirst; u < uend; u += ustride) {
;         if (u % NCHB == 0) {
;             for (int i = tid; i < PADR * (NPROJ / 8); i += NTHR) { const int r = i / (NPROJ / 8), c8 = (i - r * (NPROJ / 8)) * 8; *(u32x4*)(proj + ((size_t)u * 64 + r) * NPROJ + c8) = (u32x4){0u, 0u, 0u, 0u}; }
;         }
;         const bf16_t* ap = xb + (size_t)(u * 64 + rb4 * 16 + fr) * 1024 + kh * 512 + fq * 8;
;         const bf16_t* bp = WinT + (size_t)(NPROJ + fr) * 1024 + kh * 512 + fq * 8;
; __device__ __forceinline__ void run_phase(LAS unsigned char* lds, KP& P_, int ph) {
;     ...
;         if (!tail_first) {
;             gemm_tail(lds, xb, (const bf16_t*)(ob + OUT_WIN), 1024, NPROJ, E, hrank, hsize);
;             dt_units(lds, xb, (const bf16_t*)(ob + OUT_WIN), statB, (const float*)(ws + WS_C1IN), (const float*)(ws + WS_C2IN), (float*)(ws + WS_DT), l > 0 ? 1 : 0, (bf16_t*)(ws + WS_PROJ), hrank, hsize, 2 * hsize); }
;         else if (2 * hsize + hrank < NCHT)
;             dt_units(lds, xb, (const bf16_t*)(ob + OUT_WIN), statB, (const float*)(ws + WS_C1IN), (const float*)(ws + WS_C2IN), (float*)(ws + WS_DT), l > 0 ? 1 : 0, (bf16_t*)(ws + WS_PROJ), 2 * hsize + hrank, NCHT, NCHT);
.LBB0_915:
	v_readlane_b32 s14, v253, 45
	s_waitcnt vmcnt(0)
	v_mov_b32_e32 v22, v198
	s_mul_i32 s19, s14, 65
	s_addk_i32 s19, 64
	s_and_b32 s19, s19, 0xff
	s_sub_i32 s46, s14, 196
	s_cmp_lt_u32 s46, 4
	s_cselect_b32 s56, s46, 0
	s_cselect_b32 s46, 4, 0
	s_addk_i32 s46, 0x100
	s_addk_i32 s56, 0x100
	s_sub_i32 s56, s56, s19
	s_mov_b32 s14, s19
	s_cmp_ge_i32 s14, s46
	s_cbranch_scc1 .LBB0_928
	v_ashrrev_i32_e32 v14, 8, v22
	v_and_b32_e32 v10, 15, v22
	v_lshrrev_b32_e32 v0, 2, v22
	v_lshlrev_b32_e32 v2, 9, v14
	v_and_or_b32 v23, v0, 48, v10
	v_ashrrev_i32_e32 v3, 31, v2
	v_lshlrev_b32_e32 v10, 11, v10
	v_mov_b32_e32 v11, v1
	v_lshlrev_b64 v[8:9], 1, v[2:3]
	v_lshl_add_u64 v[10:11], s[6:7], 0, v[10:11]
	v_lshl_add_u64 v[2:3], s[36:37], 0, v[8:9]
	v_and_b32_e32 v0, 48, v22
	v_lshl_add_u64 v[8:9], v[10:11], 0, v[8:9]
	v_lshl_add_u64 v[8:9], v[8:9], 0, v[0:1]
	s_mov_b64 s[6:7], 0x600000
	v_lshl_add_u64 v[12:13], v[8:9], 0, s[6:7]
	v_lshl_or_b32 v8, v14, 6, v23
	s_movk_i32 s7, 0x50
	v_mul_lo_u32 v8, v8, s7
	v_add_u32_e32 v10, 0, v8
	v_ashrrev_i32_e32 v24, 1, v22
	v_lshlrev_b32_e32 v8, 4, v22
	v_mul_lo_u32 v9, v24, s7
	v_and_b32_e32 v8, 16, v8
	s_movk_i32 s6, 0x80
	v_add3_u32 v25, 0, v9, v8
	v_mov_b32_e32 v9, v1
	v_cmp_gt_i32_e64 s[42:43], s6, v22
	v_lshl_add_u64 v[8:9], s[86:87], 0, v[8:9]
	s_mov_b64 s[6:7], 0xee90800
	s_movk_i32 s14, 0x47ff
	v_lshl_add_u64 v[14:15], v[8:9], 0, s[6:7]
	s_mov_b64 s[6:7], 0xee93c00
	v_cmp_lt_i32_e32 vcc, s14, v22
	v_lshl_add_u64 v[16:17], v[8:9], 0, s[6:7]
	v_and_b32_e32 v8, 1, v22
	s_mov_b32 s14, s19
	v_lshl_add_u64 v[2:3], v[2:3], 0, v[0:1]
	v_cmp_eq_u32_e64 s[44:45], 1, v8
	s_xor_b64 s[6:7], vcc, -1
	v_add_u32_e32 v26, v10, v0
	s_mov_b32 s18, s14
	s_branch .LBB0_918
